# retention chunk loop: stat exchange via v_permlane32_swap instead of two ds_bpermute
# speedup vs baseline: 1.0081x; 1.0081x over previous
; DI int crow(int r, int g) { return (r & 3) + 8 * (r >> 2) + 4 * g; }
; #define MFMA32(a, b, c) __builtin_amdgcn_mfma_f32_32x32x16_bf16((a), (b), (c), 0, 0, 0)
; DI void ret_item(const Params& P, unsigned char* smem, bool samp, int b, int h) {
;     ...
;     for (int ks = 0; ks < 4; ++ks)
;       if (ks < C / 16) {
;         uaf[ks] = ld16(krt + (long)(dh * 32 + l32) * ldt + t0 + ks * 16 + g * 8);
;         ubf[ks] = ld16(vrt + (long)(eb * 32 + l32) * ldt + t0 + ks * 16 + g * 8);
;       }
;     uint2 sgv[4];
;     if (act) {
;       const u16* rp0 = grp + (t0 + nh * 32 + l32) * 1024 + eb * 32;
;       for (int i = 0; i < 4; ++i) sgv[i] = *(const uint2*)(rp0 + 4 * g + 8 * i);
;     }
;     if (act) {
;       bf16x8 qf[4];
;       {
;         const u16* p = qb + (t0 + nh * 32 + l32) * 512 + g * 8;
;         for (int ks = 0; ks < 4; ++ks) qf[ks] = ld16(p + ks * 16);
;       }
;       for (int mh = 0; mh <= nh; ++mh) {
;         bf16x8 kf[4];
;         const u16* p = kb + (t0 + mh * 32 + l32) * 512 + g * 8;
;         for (int ks = 0; ks < 4; ++ks) kf[ks] = ld16(p + ks * 16);
;         f32x16 inn = {};
;         for (int ks = 0; ks < 4; ++ks) inn = MFMA32(kf[ks], qf[ks], inn);
;         const int ncol = nh * 32 + l32;
;         for (int r = 0; r < 16; ++r) {
;           const int m = mh * 32 + crow(r, g);
;           inn[r] = (ncol >= m) ? inn[r] * ginvC : 0.f;
;         }
;         for (int s = 0; s < 2; ++s) {
;           const u16* vp = vrt + (long)(eb * 32 + l32) * ldt + t0 + mh * 32 + 16 * s + 4 * g;
;           bf16x8 vf = ld8x2(vp, vp + 8);
;           oT = MFMA32(vf, packacc8(inn, s), oT);
;         }
;       }
;       const u16* sp = sbuf + cur * (128 * SLD) + (eb * 32 + l32) * SLD + g * 8;
;       for (int ks = 0; ks < 4; ++ks) {
;         bf16x8 sf = *reinterpret_cast<const bf16x8*>(sp + ks * 16);
;         oT = MFMA32(sf, qf[ks], oT);
;       }
.Lret_loop:
	s_mul_i32 s13, s16, 0x4800
	v_add_u32_e32 v2, s13, v142
	ds_read_b128 v[228:231], v2
	ds_read_b128 v[232:235], v2 offset:32
	ds_read_b128 v[236:239], v2 offset:64
	ds_read_b128 v[240:243], v2 offset:96
	s_waitcnt vmcnt(28)
	v_mfma_f32_32x32x16_bf16 v[36:51], v[146:149], v[96:99], 0
	v_mfma_f32_32x32x16_bf16 v[36:51], v[150:153], v[92:95], v[36:51]
	v_mfma_f32_32x32x16_bf16 v[36:51], v[154:157], v[88:91], v[36:51]
	v_mfma_f32_32x32x16_bf16 v[36:51], v[158:161], v[84:87], v[36:51]
	global_load_dwordx4 v[146:149], v[122:123], off
	global_load_dwordx4 v[150:153], v[122:123], off offset:32
	global_load_dwordx4 v[154:157], v[122:123], off offset:64
	global_load_dwordx4 v[158:161], v[122:123], off offset:96
	s_waitcnt lgkmcnt(0)
	v_mfma_f32_32x32x16_bf16 v[20:35], v[228:231], v[96:99], 0
	v_mfma_f32_32x32x16_bf16 v[20:35], v[232:235], v[92:95], v[20:35]
	v_mfma_f32_32x32x16_bf16 v[20:35], v[236:239], v[88:91], v[20:35]
	v_mfma_f32_32x32x16_bf16 v[20:35], v[240:243], v[84:87], v[20:35]
	v_lshl_add_u64 v[122:123], v[122:123], 0, v[178:179]
	s_nop 3
	v_pk_mul_f32 v[36:37], v[104:105], v[36:37]
	v_pk_mul_f32 v[38:39], v[104:105], v[38:39]
	v_pk_mul_f32 v[40:41], v[104:105], v[40:41]
	v_pk_mul_f32 v[42:43], v[104:105], v[42:43]
	v_pk_mul_f32 v[44:45], v[104:105], v[44:45]
	v_pk_mul_f32 v[46:47], v[104:105], v[46:47]
	v_pk_mul_f32 v[48:49], v[104:105], v[48:49]
	v_pk_mul_f32 v[50:51], v[104:105], v[50:51]
	v_cmp_le_i32_e64 s[2:3], 0, v244
	v_cmp_le_i32_e64 s[14:15], 1, v244
	v_cmp_le_i32_e64 vcc, 2, v244
	v_cndmask_b32_e64 v36, 0, v36, s[2:3]
	v_cmp_le_i32_e64 s[2:3], 3, v244
	v_cndmask_b32_e64 v37, 0, v37, s[14:15]
	v_cmp_le_i32_e64 s[14:15], 8, v244
	v_cndmask_b32_e64 v38, 0, v38, vcc
	v_cmp_le_i32_e64 vcc, 9, v244
	v_cndmask_b32_e64 v39, 0, v39, s[2:3]
	v_cmp_le_i32_e64 s[2:3], 10, v244
	v_cndmask_b32_e64 v40, 0, v40, s[14:15]
	v_cmp_le_i32_e64 s[14:15], 11, v244
	v_cndmask_b32_e64 v41, 0, v41, vcc
	v_cmp_le_i32_e64 vcc, 16, v244
	v_cndmask_b32_e64 v42, 0, v42, s[2:3]
	v_cmp_le_i32_e64 s[2:3], 17, v244
	v_cndmask_b32_e64 v43, 0, v43, s[14:15]
	v_cmp_le_i32_e64 s[14:15], 18, v244
	v_cndmask_b32_e64 v44, 0, v44, vcc
	v_cmp_le_i32_e64 vcc, 19, v244
	v_cndmask_b32_e64 v45, 0, v45, s[2:3]
	v_cmp_le_i32_e64 s[2:3], 24, v244
	v_cndmask_b32_e64 v46, 0, v46, s[14:15]
	v_cmp_le_i32_e64 s[14:15], 25, v244
	v_cndmask_b32_e64 v47, 0, v47, vcc
	v_cmp_le_i32_e64 vcc, 26, v244
	v_cndmask_b32_e64 v48, 0, v48, s[2:3]
	v_cmp_le_i32_e64 s[2:3], 27, v244
	v_cndmask_b32_e64 v49, 0, v49, s[14:15]
	s_nop 0
	v_cndmask_b32_e64 v50, 0, v50, vcc
	v_cndmask_b32_e64 v51, 0, v51, s[2:3]
	v_cvt_pk_bf16_f32 v228, v36, v37
	v_cvt_pk_bf16_f32 v229, v38, v39
	v_cvt_pk_bf16_f32 v230, v40, v41
	v_cvt_pk_bf16_f32 v231, v42, v43
	v_cvt_pk_bf16_f32 v232, v44, v45
	v_cvt_pk_bf16_f32 v233, v46, v47
	v_cvt_pk_bf16_f32 v234, v48, v49
	v_cvt_pk_bf16_f32 v235, v50, v51
	s_waitcnt vmcnt(24)
	v_mfma_f32_32x32x16_bf16 v[36:51], v[162:165], v[96:99], 0
	v_mfma_f32_32x32x16_bf16 v[36:51], v[166:169], v[92:95], v[36:51]
	v_mfma_f32_32x32x16_bf16 v[36:51], v[170:173], v[88:91], v[36:51]
	v_mfma_f32_32x32x16_bf16 v[36:51], v[174:177], v[84:87], v[36:51]
	global_load_dwordx4 v[96:99], v[114:115], off
	global_load_dwordx4 v[92:95], v[114:115], off offset:32
	global_load_dwordx4 v[88:91], v[114:115], off offset:64
	global_load_dwordx4 v[84:87], v[114:115], off offset:96
	global_load_dwordx4 v[162:165], v[246:247], off
	global_load_dwordx4 v[166:169], v[246:247], off offset:32
	global_load_dwordx4 v[170:173], v[246:247], off offset:64
	global_load_dwordx4 v[174:177], v[246:247], off offset:96
	v_mfma_f32_32x32x16_bf16 v[20:35], v[196:199], v[228:231], v[20:35]
	v_mfma_f32_32x32x16_bf16 v[20:35], v[200:203], v[232:235], v[20:35]
	global_load_dwordx2 v[196:197], v[124:125], off
	global_load_dwordx2 v[198:199], v[124:125], off offset:16
	global_load_dwordx2 v[200:201], v[124:125], off offset:32
	global_load_dwordx2 v[202:203], v[124:125], off offset:48
	v_lshl_add_u64 v[114:115], v[114:115], 0, v[178:179]
	v_lshl_add_u64 v[246:247], v[246:247], 0, v[178:179]
	v_pk_mul_f32 v[36:37], v[104:105], v[36:37]
	v_pk_mul_f32 v[38:39], v[104:105], v[38:39]
	v_pk_mul_f32 v[40:41], v[104:105], v[40:41]
	v_pk_mul_f32 v[42:43], v[104:105], v[42:43]
	v_pk_mul_f32 v[44:45], v[104:105], v[44:45]
	v_pk_mul_f32 v[46:47], v[104:105], v[46:47]
	v_pk_mul_f32 v[48:49], v[104:105], v[48:49]
	v_pk_mul_f32 v[50:51], v[104:105], v[50:51]
	v_cmp_le_i32_e64 s[2:3], 0, v245
	v_cmp_le_i32_e64 s[14:15], 1, v245
	v_cmp_le_i32_e64 vcc, 2, v245
	v_cndmask_b32_e64 v36, 0, v36, s[2:3]
	v_cmp_le_i32_e64 s[2:3], 3, v245
	v_cndmask_b32_e64 v37, 0, v37, s[14:15]
	v_cmp_le_i32_e64 s[14:15], 8, v245
	v_cndmask_b32_e64 v38, 0, v38, vcc
	v_cmp_le_i32_e64 vcc, 9, v245
	v_cndmask_b32_e64 v39, 0, v39, s[2:3]
	v_cmp_le_i32_e64 s[2:3], 10, v245
	v_cndmask_b32_e64 v40, 0, v40, s[14:15]
	v_cmp_le_i32_e64 s[14:15], 11, v245
	v_cndmask_b32_e64 v41, 0, v41, vcc
	v_cmp_le_i32_e64 vcc, 16, v245
	v_cndmask_b32_e64 v42, 0, v42, s[2:3]
	v_cmp_le_i32_e64 s[2:3], 17, v245
	v_cndmask_b32_e64 v43, 0, v43, s[14:15]
	v_cmp_le_i32_e64 s[14:15], 18, v245
	v_cndmask_b32_e64 v44, 0, v44, vcc
	v_cmp_le_i32_e64 vcc, 19, v245
	v_cndmask_b32_e64 v45, 0, v45, s[2:3]
	v_cmp_le_i32_e64 s[2:3], 24, v245
	v_cndmask_b32_e64 v46, 0, v46, s[14:15]
	v_cmp_le_i32_e64 s[14:15], 25, v245
	v_cndmask_b32_e64 v47, 0, v47, vcc
	v_cmp_le_i32_e64 vcc, 26, v245
	v_cndmask_b32_e64 v48, 0, v48, s[2:3]
	v_cmp_le_i32_e64 s[2:3], 27, v245
	v_cndmask_b32_e64 v49, 0, v49, s[14:15]
	s_nop 0
	v_cndmask_b32_e64 v50, 0, v50, vcc
	v_cndmask_b32_e64 v51, 0, v51, s[2:3]
	v_cvt_pk_bf16_f32 v228, v36, v37
	v_cvt_pk_bf16_f32 v229, v38, v39
	v_cvt_pk_bf16_f32 v230, v40, v41
	v_cvt_pk_bf16_f32 v231, v42, v43
	v_cvt_pk_bf16_f32 v232, v44, v45
	v_cvt_pk_bf16_f32 v233, v46, v47
	v_cvt_pk_bf16_f32 v234, v48, v49
	v_cvt_pk_bf16_f32 v235, v50, v51
	s_waitcnt vmcnt(32)
; DI float bflo(unsigned u) { return __uint_as_float(u << 16); }
; DI float bfhi(unsigned u) { return __uint_as_float(u & 0xffff0000u); }
; DI uint2 pack4(float a, float b, float c, float d) { return make_uint2(pack2(a, b), pack2(c, d)); }
; #define MFMA32(a, b, c) __builtin_amdgcn_mfma_f32_32x32x16_bf16((a), (b), (c), 0, 0, 0)
; DI void ret_item(const Params& P, unsigned char* smem, bool samp, int b, int h) {
;     ...
;       float s1 = 0.f, s2 = 0.f;
;       for (int r = 0; r < 16; ++r) { s1 += oT[r]; s2 += oT[r] * oT[r]; }
;       s1 += __shfl_xor(s1, 32);
;       s2 += __shfl_xor(s2, 32);
;       if (g == 0) stat[(nh * 4 + eb) * 32 + l32] = make_float2(s1, s2);
;     }
;     __syncthreads();
;     if (act) {
;       float s1 = 0.f, s2 = 0.f;
;       for (int e = 0; e < 4; ++e) { float2 v = stat[(nh * 4 + e) * 32 + l32]; s1 += v.x; s2 += v.y; }
;       const float mean = s1 * (1.0f / 128.0f);
;       const float var = fmaxf(s2 * (1.0f / 128.0f) - mean * mean, 0.f);
;       const float rstd = rsqrtf(var + 1e-6f);
;       u16* rp = grp + (t0 + nh * 32 + l32) * 1024 + eb * 32;
;       const float* gg = P.gng + h * 128 + eb * 32;
;       for (int i = 0; i < 4; ++i) {
;         const int e = 4 * g + 8 * i;
;         const uint2 sg = sgv[i];
;         f32x4 gv = *(const f32x4*)(gg + e);
;         float r0 = (oT[4 * i] - mean) * rstd * gv[0], r1 = (oT[4 * i + 1] - mean) * rstd * gv[1];
;         float r2 = (oT[4 * i + 2] - mean) * rstd * gv[2], r3 = (oT[4 * i + 3] - mean) * rstd * gv[3];
;         *(uint2*)(rp + e) = pack4(r0 * bflo(sg.x), r1 * bfhi(sg.x), r2 * bflo(sg.y), r3 * bfhi(sg.y));
;       }
;     }
;     for (int r = 0; r < 16; ++r) S[r] *= gC;
;     for (int ks = 0; ks < 4; ++ks)
;       if (ks < C / 16) S = MFMA32(uaf[ks], ubf[ks], S);
	s_nop 1
	v_mfma_f32_32x32x16_bf16 v[20:35], v[204:207], v[228:231], v[20:35]
	v_mfma_f32_32x32x16_bf16 v[20:35], v[208:211], v[232:235], v[20:35]
	global_load_dwordx2 v[204:205], v[124:125], off offset:64
	global_load_dwordx2 v[206:207], v[124:125], off offset:80
	global_load_dwordx2 v[208:209], v[124:125], off offset:96
	global_load_dwordx2 v[210:211], v[124:125], off offset:112
	v_lshl_add_u64 v[124:125], v[124:125], 0, v[180:181]
	v_pk_mul_f32 v[4:5], v[120:121], v[4:5]
	v_pk_mul_f32 v[6:7], v[120:121], v[6:7]
	v_pk_mul_f32 v[8:9], v[120:121], v[8:9]
	v_pk_mul_f32 v[10:11], v[120:121], v[10:11]
	v_pk_mul_f32 v[12:13], v[120:121], v[12:13]
	v_pk_mul_f32 v[14:15], v[120:121], v[14:15]
	v_pk_mul_f32 v[16:17], v[120:121], v[16:17]
	v_pk_mul_f32 v[18:19], v[120:121], v[18:19]
	v_pk_mul_f32 v[36:37], v[20:21], v[20:21]
	v_pk_mul_f32 v[38:39], v[22:23], v[22:23]
	v_pk_mul_f32 v[40:41], v[24:25], v[24:25]
	v_pk_mul_f32 v[42:43], v[26:27], v[26:27]
	v_pk_mul_f32 v[44:45], v[28:29], v[28:29]
	v_pk_mul_f32 v[46:47], v[30:31], v[30:31]
	v_pk_mul_f32 v[48:49], v[32:33], v[32:33]
	v_pk_mul_f32 v[50:51], v[34:35], v[34:35]
	v_pk_add_f32 v[136:137], v[20:21], v[22:23]
	v_pk_add_f32 v[138:139], v[24:25], v[26:27]
	v_pk_add_f32 v[248:249], v[28:29], v[30:31]
	v_pk_add_f32 v[36:37], v[36:37], v[38:39]
	v_pk_add_f32 v[40:41], v[40:41], v[42:43]
	v_pk_add_f32 v[44:45], v[44:45], v[46:47]
	v_pk_add_f32 v[48:49], v[48:49], v[50:51]
	v_pk_add_f32 v[38:39], v[32:33], v[34:35]
	v_pk_add_f32 v[136:137], v[136:137], v[138:139]
	v_pk_add_f32 v[36:37], v[36:37], v[40:41]
	v_pk_add_f32 v[44:45], v[44:45], v[48:49]
	v_pk_add_f32 v[248:249], v[248:249], v[38:39]
	v_pk_add_f32 v[36:37], v[36:37], v[44:45]
	v_pk_add_f32 v[136:137], v[136:137], v[248:249]
	v_add_f32_e32 v37, v36, v37
	v_add_f32_e32 v36, v136, v137
	s_nop 0
	v_mov_b32_e32 v38, v36
	v_mov_b32_e32 v39, v37
	s_nop 1
	v_permlane32_swap_b32_e32 v36, v38
	v_permlane32_swap_b32_e32 v37, v39
	s_nop 0
	v_pk_add_f32 v[36:37], v[36:37], v[38:39]
	s_nop 0
	ds_write_b64 v143, v[36:37] offset:36864
	s_waitcnt lgkmcnt(0)
	s_barrier
; DI float bflo(unsigned u) { return __uint_as_float(u << 16); }
; DI float bfhi(unsigned u) { return __uint_as_float(u & 0xffff0000u); }
; DI uint2 pack4(float a, float b, float c, float d) { return make_uint2(pack2(a, b), pack2(c, d)); }
; #define MFMA32(a, b, c) __builtin_amdgcn_mfma_f32_32x32x16_bf16((a), (b), (c), 0, 0, 0)
; DI void ret_item(const Params& P, unsigned char* smem, bool samp, int b, int h) {
;     ...
;     if (act) {
;       float s1 = 0.f, s2 = 0.f;
;       for (int e = 0; e < 4; ++e) { float2 v = stat[(nh * 4 + e) * 32 + l32]; s1 += v.x; s2 += v.y; }
;       const float mean = s1 * (1.0f / 128.0f);
;       const float var = fmaxf(s2 * (1.0f / 128.0f) - mean * mean, 0.f);
;       const float rstd = rsqrtf(var + 1e-6f);
;       u16* rp = grp + (t0 + nh * 32 + l32) * 1024 + eb * 32;
;       const float* gg = P.gng + h * 128 + eb * 32;
;       for (int i = 0; i < 4; ++i) {
;         const int e = 4 * g + 8 * i;
;         const uint2 sg = sgv[i];
;         f32x4 gv = *(const f32x4*)(gg + e);
;         float r0 = (oT[4 * i] - mean) * rstd * gv[0], r1 = (oT[4 * i + 1] - mean) * rstd * gv[1];
;         float r2 = (oT[4 * i + 2] - mean) * rstd * gv[2], r3 = (oT[4 * i + 3] - mean) * rstd * gv[3];
;         *(uint2*)(rp + e) = pack4(r0 * bflo(sg.x), r1 * bfhi(sg.x), r2 * bflo(sg.y), r3 * bfhi(sg.y));
;       }
;     }
;     for (int r = 0; r < 16; ++r) S[r] *= gC;
;     for (int ks = 0; ks < 4; ++ks)
;       if (ks < C / 16) S = MFMA32(uaf[ks], ubf[ks], S);
;     {
;       u16* sn = sbuf + (cur ^ 1) * (128 * SLD);
;       for (int i = 0; i < 4; ++i) {
;         const int d0 = dh * 32 + 4 * g + 8 * i;
;         *(uint2*)(sn + (eb * 32 + l32) * SLD + d0) = pack4(S[4 * i], S[4 * i + 1], S[4 * i + 2], S[4 * i + 3]);
;       }
;     }
;     __syncthreads();
;     cur ^= 1;
	v_add_u32_e32 v2, 0x9000, v145
	ds_read2_b64 v[42:45], v2 offset1:32
	ds_read2_b64 v[46:49], v2 offset0:64 offset1:96
	s_waitcnt vmcnt(20)
	v_mfma_f32_32x32x16_bf16 v[4:19], v[76:79], v[80:83], v[4:19]
	v_mfma_f32_32x32x16_bf16 v[4:19], v[68:71], v[72:75], v[4:19]
	v_mfma_f32_32x32x16_bf16 v[4:19], v[60:63], v[64:67], v[4:19]
	v_mfma_f32_32x32x16_bf16 v[4:19], v[52:55], v[56:59], v[4:19]
	global_load_dwordx4 v[76:79], v[108:109], off
	global_load_dwordx4 v[68:71], v[108:109], off offset:32
	global_load_dwordx4 v[60:63], v[108:109], off offset:64
	global_load_dwordx4 v[52:55], v[108:109], off offset:96
	global_load_dwordx4 v[80:83], v[110:111], off
	global_load_dwordx4 v[72:75], v[110:111], off offset:32
	global_load_dwordx4 v[64:67], v[110:111], off offset:64
	global_load_dwordx4 v[56:59], v[110:111], off offset:96
	v_lshl_add_u64 v[108:109], v[108:109], 0, v[180:181]
	v_lshl_add_u64 v[110:111], v[110:111], 0, v[180:181]
	s_waitcnt lgkmcnt(0)
	v_pk_add_f32 v[36:37], v[42:43], v[44:45]
	v_pk_add_f32 v[36:37], v[36:37], v[46:47]
	v_pk_add_f32 v[36:37], v[36:37], v[48:49]
	v_pk_mul_f32 v[36:37], v[36:37], s[84:85] op_sel_hi:[1,0]
	v_fma_f32 v2, -v36, v36, v37
	v_max_f32_e32 v2, 0, v2
	v_add_f32_e32 v2, 0x358637bd, v2
	v_rsq_f32_e32 v2, v2
	v_pk_add_f32 v[20:21], v[20:21], v[36:37] op_sel_hi:[1,0] neg_lo:[0,1] neg_hi:[0,1]
	v_pk_add_f32 v[22:23], v[22:23], v[36:37] op_sel_hi:[1,0] neg_lo:[0,1] neg_hi:[0,1]
	v_pk_add_f32 v[24:25], v[24:25], v[36:37] op_sel_hi:[1,0] neg_lo:[0,1] neg_hi:[0,1]
	v_pk_add_f32 v[26:27], v[26:27], v[36:37] op_sel_hi:[1,0] neg_lo:[0,1] neg_hi:[0,1]
	v_pk_add_f32 v[28:29], v[28:29], v[36:37] op_sel_hi:[1,0] neg_lo:[0,1] neg_hi:[0,1]
	v_pk_add_f32 v[30:31], v[30:31], v[36:37] op_sel_hi:[1,0] neg_lo:[0,1] neg_hi:[0,1]
	v_pk_add_f32 v[32:33], v[32:33], v[36:37] op_sel_hi:[1,0] neg_lo:[0,1] neg_hi:[0,1]
	v_pk_add_f32 v[34:35], v[34:35], v[36:37] op_sel_hi:[1,0] neg_lo:[0,1] neg_hi:[0,1]
	v_pk_mul_f32 v[20:21], v[20:21], v[2:3] op_sel_hi:[1,0]
	v_pk_mul_f32 v[22:23], v[22:23], v[2:3] op_sel_hi:[1,0]
	v_pk_mul_f32 v[24:25], v[24:25], v[2:3] op_sel_hi:[1,0]
	v_pk_mul_f32 v[26:27], v[26:27], v[2:3] op_sel_hi:[1,0]
	v_pk_mul_f32 v[28:29], v[28:29], v[2:3] op_sel_hi:[1,0]
	v_pk_mul_f32 v[30:31], v[30:31], v[2:3] op_sel_hi:[1,0]
	v_pk_mul_f32 v[32:33], v[32:33], v[2:3] op_sel_hi:[1,0]
	v_pk_mul_f32 v[34:35], v[34:35], v[2:3] op_sel_hi:[1,0]
	v_pk_mul_f32 v[20:21], v[212:213], v[20:21]
	v_pk_mul_f32 v[22:23], v[214:215], v[22:23]
	v_lshlrev_b32_e32 v40, 16, v134
	v_and_b32_e32 v41, 0xffff0000, v134
	v_lshlrev_b32_e32 v42, 16, v135
	v_and_b32_e32 v43, 0xffff0000, v135
	v_pk_mul_f32 v[20:21], v[20:21], v[40:41]
	v_pk_mul_f32 v[22:23], v[22:23], v[42:43]
	v_cvt_pk_bf16_f32 v44, v20, v21
	v_cvt_pk_bf16_f32 v45, v22, v23
	v_pk_mul_f32 v[24:25], v[216:217], v[24:25]
	v_pk_mul_f32 v[26:27], v[218:219], v[26:27]
	v_lshlrev_b32_e32 v40, 16, v132
	v_and_b32_e32 v41, 0xffff0000, v132
	v_lshlrev_b32_e32 v42, 16, v133
	v_and_b32_e32 v43, 0xffff0000, v133
	v_pk_mul_f32 v[24:25], v[24:25], v[40:41]
	v_pk_mul_f32 v[26:27], v[26:27], v[42:43]
	v_cvt_pk_bf16_f32 v46, v24, v25
	v_cvt_pk_bf16_f32 v47, v26, v27
	v_pk_mul_f32 v[28:29], v[220:221], v[28:29]
	v_pk_mul_f32 v[30:31], v[222:223], v[30:31]
	v_lshlrev_b32_e32 v40, 16, v130
	v_and_b32_e32 v41, 0xffff0000, v130
	v_lshlrev_b32_e32 v42, 16, v131
	v_and_b32_e32 v43, 0xffff0000, v131
	v_pk_mul_f32 v[28:29], v[28:29], v[40:41]
	v_pk_mul_f32 v[30:31], v[30:31], v[42:43]
	v_cvt_pk_bf16_f32 v48, v28, v29
	v_cvt_pk_bf16_f32 v49, v30, v31
	v_pk_mul_f32 v[32:33], v[224:225], v[32:33]
	v_pk_mul_f32 v[34:35], v[226:227], v[34:35]
	v_lshlrev_b32_e32 v40, 16, v128
	v_and_b32_e32 v41, 0xffff0000, v128
	v_lshlrev_b32_e32 v42, 16, v129
	v_and_b32_e32 v43, 0xffff0000, v129
	v_pk_mul_f32 v[32:33], v[32:33], v[40:41]
	v_pk_mul_f32 v[34:35], v[34:35], v[42:43]
	v_cvt_pk_bf16_f32 v50, v32, v33
	v_cvt_pk_bf16_f32 v51, v34, v35
	global_store_dwordx2 v[126:127], v[44:45], off
	global_store_dwordx2 v[126:127], v[46:47], off offset:16
	global_store_dwordx2 v[126:127], v[48:49], off offset:32
	global_store_dwordx2 v[126:127], v[50:51], off offset:48
	v_lshl_add_u64 v[126:127], v[126:127], 0, v[140:141]
	global_load_dwordx2 v[134:135], v[126:127], off
	global_load_dwordx2 v[132:133], v[126:127], off offset:16
	global_load_dwordx2 v[130:131], v[126:127], off offset:32
	global_load_dwordx2 v[128:129], v[126:127], off offset:48
	v_cvt_pk_bf16_f32 v36, v4, v5
	v_cvt_pk_bf16_f32 v37, v6, v7
	v_cvt_pk_bf16_f32 v38, v8, v9
	v_cvt_pk_bf16_f32 v39, v10, v11
	v_cvt_pk_bf16_f32 v40, v12, v13
	v_cvt_pk_bf16_f32 v41, v14, v15
	v_cvt_pk_bf16_f32 v42, v16, v17
	v_cvt_pk_bf16_f32 v43, v18, v19
	s_xor_b32 s16, s16, 1
	s_mul_i32 s13, s16, 0x4800
	s_add_i32 s90, s90, 1
	v_add_u32_e32 v2, s13, v119
	s_cmpk_lg_i32 s90, 0x80
	ds_write2_b64 v2, v[36:37], v[38:39] offset1:2
	ds_write2_b64 v2, v[40:41], v[42:43] offset0:4 offset1:6
	s_waitcnt lgkmcnt(0)
	s_barrier
	s_cbranch_scc1 .Lret_loop
	s_waitcnt vmcnt(0)
	s_branch .LBB0_287
